# MLA main loop: K/V staged by LDS-DMA into 4-buffer ring, V frags read as b128 via K-row permutation; T=8 lazy rescale
# speedup vs baseline: 1.0160x; 1.0160x over previous
.LBB0_1009:
	s_not_b32 s0, s42
	s_andn2_b32 s7, 31, s42
	s_lshr_b32 s68, s0, 8
	s_lshr_b32 s6, s0, 5
	s_bfe_u32 s43, s0, 0x30005
	s_lshl_b64 s[0:1], s[68:69], 13
	s_lshl_b32 s12, s7, 8
	s_add_u32 s12, s12, s36
	s_addc_u32 s13, 0, s40
	s_add_u32 s0, s12, s0
	s_addc_u32 s1, s13, s1
	s_mul_i32 s12, s1, 0x600
	s_mul_hi_u32 s13, s0, 0x600
	s_add_i32 s13, s13, s12
	s_mul_i32 s12, s0, 0x600
	s_add_u32 s12, s14, s12
	s_addc_u32 s13, s15, s13
	s_mul_i32 s44, s43, 0xc0
	s_add_u32 s12, s12, s44
	s_addc_u32 s13, s13, 0
	s_mul_hi_u32 s45, s6, 0x180000
	s_mul_i32 s6, s6, 0x180000
	s_add_u32 s44, s18, s6
	s_addc_u32 s45, s19, s45
	s_sub_u32 s56, s44, s18
	s_lshl_b32 s6, s43, 6
	s_lshl_b64 s[46:47], s[68:69], 23
	s_add_u32 s46, s22, s46
	s_addc_u32 s47, s23, s47
	s_lshl_b32 s43, s43, 20
	s_add_u32 s46, s46, s43
	s_mov_b32 s43, 0x2aaaaaab
	v_mul_hi_i32 v3, v2, s43
	v_lshrrev_b32_e32 v4, 31, v3
	v_ashrrev_i32_e32 v3, 1, v3
	v_add_u32_e32 v0, 0x200, v2
	v_cmp_gt_i32_e32 vcc, s83, v2
	v_add_u32_e32 v20, v3, v4
	v_mul_lo_u32 v3, v20, 12
	v_cndmask_b32_e32 v0, v2, v0, vcc
	v_sub_u32_e32 v21, v2, v3
	v_mul_hi_i32 v3, v0, s43
	v_lshrrev_b32_e32 v4, 31, v3
	v_ashrrev_i32_e32 v3, 1, v3
	v_add_u32_e32 v22, v3, v4
	v_mul_lo_u32 v3, v22, 12
	v_mov_b64_e32 v[4:5], s[44:45]
	v_lshlrev_b32_e32 v8, 3, v21
	v_sub_u32_e32 v23, v0, v3
	v_ashrrev_i32_e32 v16, 3, v2
	v_mad_i64_i32 v[6:7], s[44:45], v20, s96, v[4:5]
	v_ashrrev_i32_e32 v9, 31, v8
	v_lshl_add_u64 v[164:165], v[8:9], 1, v[6:7]
	v_lshlrev_b32_e32 v6, 3, v23
	v_ashrrev_i32_e32 v17, 31, v16
	s_movk_i32 s43, 0x3000
	s_addc_u32 s47, s47, 0
	s_sub_u32 s57, s46, s18
	v_mad_i64_i32 v[4:5], s[44:45], v22, s96, v[4:5]
	v_ashrrev_i32_e32 v7, 31, v6
	v_lshlrev_b64 v[12:13], 14, v[16:17]
	v_lshlrev_b32_e32 v0, 4, v2
	v_and_b32_e32 v163, 31, v2
	v_bfe_u32 v17, v2, 5, 1
	v_add_co_u32_e32 v2, vcc, s43, v164
	v_lshl_add_u64 v[166:167], v[6:7], 1, v[4:5]
	v_lshl_add_u64 v[12:13], s[46:47], 0, v[12:13]
	v_and_b32_e32 v0, 0x70, v0
	v_addc_co_u32_e32 v3, vcc, 0, v165, vcc
	v_lshl_add_u64 v[168:169], v[12:13], 0, v[0:1]
	v_add_co_u32_e32 v18, vcc, s43, v166
	v_addc_co_u32_e32 v19, vcc, 0, v167, vcc
	v_mul_u32_u24_e32 v2, 0x600, v163
	v_mov_b32_e32 v3, v1
	v_lshl_add_u64 v[2:3], s[12:13], 0, v[2:3]
	v_lshlrev_b32_e32 v170, 4, v17
	v_mov_b32_e32 v171, v1
	v_lshl_add_u64 v[2:3], v[2:3], 0, v[170:171]
	global_load_dwordx4 v[82:85], v[2:3], off
	global_load_dwordx4 v[90:93], v[2:3], off offset:32
	global_load_dwordx4 v[94:97], v[2:3], off offset:64
	global_load_dwordx4 v[98:101], v[2:3], off offset:96
	global_load_dwordx4 v[106:109], v[2:3], off offset:128
	global_load_dwordx4 v[110:113], v[2:3], off offset:160
	s_movk_i32 s46, 0xd0
	v_mul_lo_u32 v2, v20, s46
	v_mul_lo_u32 v3, v22, s46
	v_lshl_add_u32 v2, v21, 4, v2
	v_lshl_add_u32 v3, v23, 4, v3
	v_add_u32_e32 v171, 0, v2
	v_add_u32_e32 v174, 0, v3
	v_mad_u64_u32 v[2:3], s[44:45], v16, s87, v[0:1]
	v_mad_u32_u24 v177, v163, s46, 0
	s_movk_i32 s44, 0xffb8
	v_mad_i32_i24 v178, v163, s44, v177
	s_movk_i32 s45, 0x48
	v_add_u32_e32 v175, 0, v2
	v_mad_u32_u24 v179, v163, s45, v178
	v_lshlrev_b32_e32 v162, 3, v17
	v_add_u32_e32 v176, 0x6800, v175
	v_mad_i32_i24 v2, v163, s44, v179
	v_mov_b32_e32 v34, v1
	v_mov_b32_e32 v35, v1
	s_lshl_b32 s43, s7, 2
	v_mov_b32_e32 v0, v1
	v_mov_b32_e32 v36, v1
	v_mov_b32_e32 v37, v1
	v_mov_b32_e32 v38, v1
	v_mov_b32_e32 v39, v1
	v_mov_b32_e32 v40, v1
	v_mov_b32_e32 v41, v1
	v_mov_b32_e32 v42, v1
	v_mov_b32_e32 v43, v1
	v_mov_b32_e32 v44, v1
	v_mov_b32_e32 v45, v1
	v_mov_b32_e32 v46, v1
	v_mov_b32_e32 v47, v1
	v_mov_b32_e32 v48, v1
	v_mov_b32_e32 v49, v1
	v_add_u32_e32 v181, v2, v162
	v_mov_b64_e32 v[18:19], v[34:35]
	s_add_i32 s7, s43, 4
	s_add_i32 s12, s43, s41
	s_mov_b32 s13, 3
	s_or_b32 s43, s43, 3
	v_mov_b32_e32 v180, 0
	v_mov_b64_e32 v[20:21], v[36:37]
	v_mov_b64_e32 v[22:23], v[38:39]
	v_mov_b64_e32 v[24:25], v[40:41]
	v_mov_b64_e32 v[26:27], v[42:43]
	v_mov_b64_e32 v[28:29], v[44:45]
	v_mov_b64_e32 v[30:31], v[46:47]
	v_mov_b64_e32 v[32:33], v[48:49]
	v_mov_b64_e32 v[172:173], v[0:1]
	v_mov_b64_e32 v[2:3], v[34:35]
	v_mov_b64_e32 v[4:5], v[36:37]
	v_mov_b64_e32 v[6:7], v[38:39]
	v_mov_b64_e32 v[8:9], v[40:41]
	v_mov_b64_e32 v[10:11], v[42:43]
	v_mov_b64_e32 v[12:13], v[44:45]
	v_mov_b64_e32 v[14:15], v[46:47]
	v_mov_b64_e32 v[16:17], v[48:49]
	v_readfirstlane_b32 s32, v228
	v_and_b32_e32 v199, 63, v228
	s_nop 2
	s_lshr_b32 s32, s32, 6
	s_mov_b32 s67, 0xb000
	s_mov_b32 s98, s32
	s_cmp_lt_u32 s98, 13
	s_cbranch_scc1 .Ldma_isk_0
	s_cmp_lt_u32 s98, 22
	s_cbranch_scc1 .Ldma_isv_0
	s_sub_i32 s98, s98, 22
.Ldma_isk_0:
	s_lshl_b32 s99, s98, 6
	v_add_u32_e32 v210, s99, v199
	v_mul_u32_u24_e32 v211, 0x13b2, v210
	v_lshrrev_b32_e32 v211, 16, v211
	v_mul_u32_u24_e32 v200, 13, v211
	v_sub_u32_e32 v200, v210, v200
	v_min_u32_e32 v200, 11, v200
	v_mul_u32_u24_e32 v211, 0xc0, v211
	v_lshl_add_u32 v202, v200, 4, v211
	v_add_u32_e32 v202, s56, v202
	v_mov_b32_e32 v196, 0x3000
	s_lshl_b32 s60, s98, 10
	s_branch .Ldma_sdone_0
.Ldma_isv_0:
	s_sub_i32 s98, s98, 13
	s_lshl_b32 s99, s98, 6
	v_add_u32_e32 v210, s99, v199
	v_mul_u32_u24_e32 v211, 0x1c72, v210
	v_lshrrev_b32_e32 v211, 16, v211
	v_mul_u32_u24_e32 v200, 9, v211
	v_sub_u32_e32 v200, v210, v200
	v_min_u32_e32 v200, 7, v200
	v_lshlrev_b32_e32 v211, 14, v211
	v_lshl_add_u32 v202, v200, 4, v211
	v_add_u32_e32 v202, s57, v202
	v_mov_b32_e32 v196, 0x80
	s_lshl_b32 s60, s98, 10
	s_addk_i32 s60, 0x3400
.Ldma_sdone_0:
	s_add_i32 s98, s32, 8
	s_cmp_lt_u32 s98, 13
	s_cbranch_scc1 .Ldma_isk_1
	s_cmp_lt_u32 s98, 22
	s_cbranch_scc1 .Ldma_isv_1
	s_sub_i32 s98, s98, 22
.Ldma_isk_1:
	s_lshl_b32 s99, s98, 6
	v_add_u32_e32 v210, s99, v199
	v_mul_u32_u24_e32 v211, 0x13b2, v210
	v_lshrrev_b32_e32 v211, 16, v211
	v_mul_u32_u24_e32 v200, 13, v211
	v_sub_u32_e32 v200, v210, v200
	v_min_u32_e32 v200, 11, v200
	v_mul_u32_u24_e32 v211, 0xc0, v211
	v_lshl_add_u32 v203, v200, 4, v211
	v_add_u32_e32 v203, s56, v203
	v_mov_b32_e32 v197, 0x3000
	s_lshl_b32 s61, s98, 10
	s_branch .Ldma_sdone_1
.Ldma_isv_1:
	s_sub_i32 s98, s98, 13
	s_lshl_b32 s99, s98, 6
	v_add_u32_e32 v210, s99, v199
	v_mul_u32_u24_e32 v211, 0x1c72, v210
	v_lshrrev_b32_e32 v211, 16, v211
	v_mul_u32_u24_e32 v200, 9, v211
	v_sub_u32_e32 v200, v210, v200
	v_min_u32_e32 v200, 7, v200
	v_lshlrev_b32_e32 v211, 14, v211
	v_lshl_add_u32 v203, v200, 4, v211
	v_add_u32_e32 v203, s57, v203
	v_mov_b32_e32 v197, 0x80
	s_lshl_b32 s61, s98, 10
	s_addk_i32 s61, 0x3400
.Ldma_sdone_1:
	s_add_i32 s98, s32, 16
	s_cmp_lt_u32 s98, 13
	s_cbranch_scc1 .Ldma_isk_2
	s_cmp_lt_u32 s98, 22
	s_cbranch_scc1 .Ldma_isv_2
	s_sub_i32 s98, s98, 22
.Ldma_isk_2:
	s_lshl_b32 s99, s98, 6
	v_add_u32_e32 v210, s99, v199
	v_mul_u32_u24_e32 v211, 0x13b2, v210
	v_lshrrev_b32_e32 v211, 16, v211
	v_mul_u32_u24_e32 v200, 13, v211
	v_sub_u32_e32 v200, v210, v200
	v_min_u32_e32 v200, 11, v200
	v_mul_u32_u24_e32 v211, 0xc0, v211
	v_lshl_add_u32 v204, v200, 4, v211
	v_add_u32_e32 v204, s56, v204
	v_mov_b32_e32 v198, 0x3000
	s_lshl_b32 s66, s98, 10
	s_branch .Ldma_sdone_2
.Ldma_isv_2:
	s_sub_i32 s98, s98, 13
	s_lshl_b32 s99, s98, 6
	v_add_u32_e32 v210, s99, v199
	v_mul_u32_u24_e32 v211, 0x1c72, v210
	v_lshrrev_b32_e32 v211, 16, v211
	v_mul_u32_u24_e32 v200, 9, v211
	v_sub_u32_e32 v200, v210, v200
	v_min_u32_e32 v200, 7, v200
	v_lshlrev_b32_e32 v211, 14, v211
	v_lshl_add_u32 v204, v200, 4, v211
	v_add_u32_e32 v204, s57, v204
	v_mov_b32_e32 v198, 0x80
	s_lshl_b32 s66, s98, 10
	s_addk_i32 s66, 0x3400
.Ldma_sdone_2:
	v_lshrrev_b32_e32 v207, 2, v163
	v_lshrrev_b32_e32 v201, 3, v163
	v_xor_b32_e32 v207, v207, v201
	v_and_b32_e32 v207, 1, v207
	v_mul_u32_u24_e32 v207, 12, v207
	v_xor_b32_e32 v207, v163, v207
	v_mul_u32_u24_e32 v205, 0xd0, v207
	v_mul_u32_u24_e32 v206, 0x90, v163
	v_add_u32_e32 v206, 0x3400, v206
	v_add_u32_e32 v206, v206, v170
	s_mov_b32 m0, s60
	s_nop 0
	global_load_lds_dwordx4 v202, s[18:19]
	s_mov_b32 m0, s61
	s_nop 0
	global_load_lds_dwordx4 v203, s[18:19]
	s_mov_b32 m0, s66
	s_nop 0
	global_load_lds_dwordx4 v204, s[18:19]
	v_add_u32_e32 v202, v196, v202
	v_add_u32_e32 v203, v197, v203
	v_add_u32_e32 v204, v198, v204
	s_add_u32 m0, s60, 0x5800
	s_nop 0
	global_load_lds_dwordx4 v202, s[18:19]
	s_add_u32 m0, s61, 0x5800
	s_nop 0
	global_load_lds_dwordx4 v203, s[18:19]
	s_add_u32 m0, s66, 0x5800
	s_nop 0
	global_load_lds_dwordx4 v204, s[18:19]
	v_add_u32_e32 v202, v196, v202
	v_add_u32_e32 v203, v197, v203
	v_add_u32_e32 v204, v198, v204
	s_mov_b32 s13, 0
	s_waitcnt vmcnt(3)
	s_barrier
	s_branch .Ldma_top
.Ldma_top:
	s_add_u32 m0, s60, 0xb000
	s_nop 0
	global_load_lds_dwordx4 v202, s[18:19]
	s_add_u32 m0, s61, 0xb000
	s_nop 0
	global_load_lds_dwordx4 v203, s[18:19]
	s_add_u32 m0, s66, 0xb000
	s_nop 0
	global_load_lds_dwordx4 v204, s[18:19]
	s_add_i32 s44, s13, 3
	s_cmp_lt_u32 s44, s7
	s_cbranch_scc0 .Ldma_noadv_0
	v_add_u32_e32 v202, v196, v202
	v_add_u32_e32 v203, v197, v203
	v_add_u32_e32 v204, v198, v204
.Ldma_noadv_0:
	s_mov_b32 s44, s13
	s_cmp_gt_i32 s44, s12
	s_cbranch_scc1 .Ldma_skip_0
	v_add_u32_e32 v0, v205, v170
	ds_read_b128 v[50:53], v0
	ds_read_b128 v[130:133], v0 offset:32
	ds_read_b128 v[134:137], v0 offset:6656
	ds_read_b128 v[138:141], v0 offset:6688
	ds_read_b128 v[142:145], v0 offset:64
	ds_read_b128 v[146:149], v0 offset:96
	ds_read_b128 v[150:153], v0 offset:6720
	ds_read_b128 v[154:157], v0 offset:6752
	ds_read_b128 v[158:161], v0 offset:128
	ds_read_b128 v[182:185], v0 offset:160
	ds_read_b128 v[186:189], v0 offset:6784
	ds_read_b128 v[190:193], v0 offset:6816
	s_waitcnt lgkmcnt(11)
	v_mfma_f32_32x32x16_bf16 v[66:81], v[50:53], v[82:85], v[34:49]
	v_mov_b32_e32 v0, v206
	s_waitcnt lgkmcnt(9)
	v_mfma_f32_32x32x16_bf16 v[50:65], v[134:137], v[82:85], v[34:49]
	v_mfma_f32_32x32x16_bf16 v[66:81], v[130:133], v[90:93], v[66:81]
	s_waitcnt lgkmcnt(8)
	v_mfma_f32_32x32x16_bf16 v[50:65], v[138:141], v[90:93], v[50:65]
	s_waitcnt lgkmcnt(7)
	v_mfma_f32_32x32x16_bf16 v[66:81], v[142:145], v[94:97], v[66:81]
	s_waitcnt lgkmcnt(5)
	v_mfma_f32_32x32x16_bf16 v[50:65], v[150:153], v[94:97], v[50:65]
	v_mfma_f32_32x32x16_bf16 v[66:81], v[146:149], v[98:101], v[66:81]
	s_waitcnt lgkmcnt(4)
	v_mfma_f32_32x32x16_bf16 v[50:65], v[154:157], v[98:101], v[50:65]
	ds_read_b128 v[154:157], v0
	ds_read_b128 v[146:149], v0 offset:32
	s_waitcnt lgkmcnt(5)
	v_mfma_f32_32x32x16_bf16 v[66:81], v[158:161], v[106:109], v[66:81]
	ds_read_b128 v[158:161], v0 offset:4608
	ds_read_b128 v[150:153], v0 offset:4640
	ds_read_b128 v[142:145], v0 offset:64
	ds_read_b128 v[138:141], v0 offset:4672
	ds_read_b128 v[134:137], v0 offset:96
	ds_read_b128 v[130:133], v0 offset:4704
	s_waitcnt lgkmcnt(9)
	v_mfma_f32_32x32x16_bf16 v[50:65], v[186:189], v[106:109], v[50:65]
	v_mfma_f32_32x32x16_bf16 v[66:81], v[182:185], v[110:113], v[66:81]
	s_waitcnt lgkmcnt(8)
	v_mfma_f32_32x32x16_bf16 v[50:65], v[190:193], v[110:113], v[50:65]
	s_nop 9
	v_max_f32_e32 v0, v67, v67
	v_max_f32_e32 v182, v66, v66
	v_max_f32_e32 v0, v182, v0
	v_max3_f32 v182, v68, v69, v51
	v_max3_f32 v0, v0, v50, v52
	v_max3_f32 v0, v0, v53, v70
	v_max3_f32 v182, v182, v72, v73
	v_max3_f32 v0, v0, v71, v54
	v_max3_f32 v182, v182, v56, v57
	v_max3_f32 v0, v0, v55, v74
	v_max3_f32 v182, v182, v76, v77
	v_max3_f32 v0, v0, v75, v58
	v_max3_f32 v182, v182, v60, v61
	v_max3_f32 v0, v0, v59, v78
	v_max3_f32 v182, v182, v80, v81
	v_max3_f32 v0, v0, v79, v62
	v_max3_f32 v182, v182, v64, v65
	v_max3_f32 v0, v0, v63, v182
	v_mov_b32_e32 v182, v0
	s_nop 1
	v_permlane32_swap_b32_e32 v0, v182
	v_max_f32_e32 v182, v182, v182
	v_max_f32_e32 v0, v0, v0
	v_max_f32_e32 v0, v0, v182
	v_cmp_lt_f32_e32 vcc, 0x41000000, v0
	s_cbranch_vccz .Ldma_join_0
	v_max_f32_e32 v0, v0, v0
	v_max_f32_e32 v34, 0, v0
	v_exp_f32_e64 v0, -v34
	v_add_f32_e32 v180, v180, v34
	v_sub_f32_e32 v66, v66, v34
	v_sub_f32_e32 v67, v67, v34
	v_sub_f32_e32 v68, v68, v34
	v_sub_f32_e32 v69, v69, v34
	v_sub_f32_e32 v70, v70, v34
	v_sub_f32_e32 v71, v71, v34
	v_sub_f32_e32 v72, v72, v34
	v_sub_f32_e32 v73, v73, v34
	v_sub_f32_e32 v74, v74, v34
	v_sub_f32_e32 v75, v75, v34
	v_sub_f32_e32 v76, v76, v34
	v_sub_f32_e32 v77, v77, v34
	v_sub_f32_e32 v78, v78, v34
	v_sub_f32_e32 v79, v79, v34
	v_sub_f32_e32 v80, v80, v34
	v_sub_f32_e32 v81, v81, v34
	v_sub_f32_e32 v50, v50, v34
	v_sub_f32_e32 v51, v51, v34
	v_sub_f32_e32 v52, v52, v34
	v_sub_f32_e32 v53, v53, v34
	v_sub_f32_e32 v54, v54, v34
	v_sub_f32_e32 v55, v55, v34
	v_sub_f32_e32 v56, v56, v34
	v_sub_f32_e32 v57, v57, v34
	v_sub_f32_e32 v58, v58, v34
	v_sub_f32_e32 v59, v59, v34
	v_sub_f32_e32 v60, v60, v34
	v_sub_f32_e32 v61, v61, v34
	v_sub_f32_e32 v62, v62, v34
	v_sub_f32_e32 v63, v63, v34
	v_sub_f32_e32 v64, v64, v34
	v_sub_f32_e32 v65, v65, v34
	v_sub_f32_e32 v34, 0, v180
	v_pk_mul_f32 v[32:33], v[32:33], v[0:1] op_sel_hi:[1,0]
	v_pk_mul_f32 v[30:31], v[30:31], v[0:1] op_sel_hi:[1,0]
	v_pk_mul_f32 v[28:29], v[28:29], v[0:1] op_sel_hi:[1,0]
	v_pk_mul_f32 v[26:27], v[26:27], v[0:1] op_sel_hi:[1,0]
	v_pk_mul_f32 v[24:25], v[24:25], v[0:1] op_sel_hi:[1,0]
	v_pk_mul_f32 v[22:23], v[22:23], v[0:1] op_sel_hi:[1,0]
	v_pk_mul_f32 v[20:21], v[20:21], v[0:1] op_sel_hi:[1,0]
	v_pk_mul_f32 v[18:19], v[18:19], v[0:1] op_sel_hi:[1,0]
	v_pk_mul_f32 v[16:17], v[16:17], v[0:1] op_sel_hi:[1,0]
	v_pk_mul_f32 v[14:15], v[14:15], v[0:1] op_sel_hi:[1,0]
	v_pk_mul_f32 v[12:13], v[12:13], v[0:1] op_sel_hi:[1,0]
	v_pk_mul_f32 v[10:11], v[10:11], v[0:1] op_sel_hi:[1,0]
	v_pk_mul_f32 v[8:9], v[8:9], v[0:1] op_sel_hi:[1,0]
	v_pk_mul_f32 v[6:7], v[6:7], v[0:1] op_sel_hi:[1,0]
	v_pk_mul_f32 v[4:5], v[4:5], v[0:1] op_sel_hi:[1,0]
	v_pk_mul_f32 v[2:3], v[2:3], v[0:1] op_sel_hi:[1,0]
	v_pk_mul_f32 v[172:173], v[172:173], v[0:1] op_sel_hi:[1,0]
	v_mov_b32_e32 v35, v34
	v_mov_b32_e32 v36, v34
	v_mov_b32_e32 v37, v34
	v_mov_b32_e32 v38, v34
	v_mov_b32_e32 v39, v34
	v_mov_b32_e32 v40, v34
	v_mov_b32_e32 v41, v34
	v_mov_b32_e32 v42, v34
	v_mov_b32_e32 v43, v34
	v_mov_b32_e32 v44, v34
	v_mov_b32_e32 v45, v34
	v_mov_b32_e32 v46, v34
	v_mov_b32_e32 v47, v34
	v_mov_b32_e32 v48, v34
	v_mov_b32_e32 v49, v34

.Ldma_skip_0:
	s_waitcnt vmcnt(3)
	s_barrier
	s_add_u32 m0, s60, 0x10800
	s_nop 0
	global_load_lds_dwordx4 v202, s[18:19]
	s_add_u32 m0, s61, 0x10800
	s_nop 0
	global_load_lds_dwordx4 v203, s[18:19]
	s_add_u32 m0, s66, 0x10800
	s_nop 0
	global_load_lds_dwordx4 v204, s[18:19]
	s_add_i32 s44, s13, 4
	s_cmp_lt_u32 s44, s7
	s_cbranch_scc0 .Ldma_noadv_1
	v_add_u32_e32 v202, v196, v202
	v_add_u32_e32 v203, v197, v203
	v_add_u32_e32 v204, v198, v204
.Ldma_noadv_1:
	s_add_i32 s44, s13, 1
	s_cmp_gt_i32 s44, s12
	s_cbranch_scc1 .Ldma_skip_1
	v_add_u32_e32 v0, v205, v170
	ds_read_b128 v[50:53], v0 offset:22528
	ds_read_b128 v[130:133], v0 offset:22560
	ds_read_b128 v[134:137], v0 offset:29184
	ds_read_b128 v[138:141], v0 offset:29216
	ds_read_b128 v[142:145], v0 offset:22592
	ds_read_b128 v[146:149], v0 offset:22624
	ds_read_b128 v[150:153], v0 offset:29248
	ds_read_b128 v[154:157], v0 offset:29280
	ds_read_b128 v[158:161], v0 offset:22656
	ds_read_b128 v[182:185], v0 offset:22688
	ds_read_b128 v[186:189], v0 offset:29312
	ds_read_b128 v[190:193], v0 offset:29344
	s_waitcnt lgkmcnt(11)
	v_mfma_f32_32x32x16_bf16 v[66:81], v[50:53], v[82:85], v[34:49]
	v_mov_b32_e32 v0, v206
	s_waitcnt lgkmcnt(9)
	v_mfma_f32_32x32x16_bf16 v[50:65], v[134:137], v[82:85], v[34:49]
	v_mfma_f32_32x32x16_bf16 v[66:81], v[130:133], v[90:93], v[66:81]
	s_waitcnt lgkmcnt(8)
	v_mfma_f32_32x32x16_bf16 v[50:65], v[138:141], v[90:93], v[50:65]
	s_waitcnt lgkmcnt(7)
	v_mfma_f32_32x32x16_bf16 v[66:81], v[142:145], v[94:97], v[66:81]
	s_waitcnt lgkmcnt(5)
	v_mfma_f32_32x32x16_bf16 v[50:65], v[150:153], v[94:97], v[50:65]
	v_mfma_f32_32x32x16_bf16 v[66:81], v[146:149], v[98:101], v[66:81]
	s_waitcnt lgkmcnt(4)
	v_mfma_f32_32x32x16_bf16 v[50:65], v[154:157], v[98:101], v[50:65]
	ds_read_b128 v[154:157], v0 offset:22528
	ds_read_b128 v[146:149], v0 offset:22560
	s_waitcnt lgkmcnt(5)
	v_mfma_f32_32x32x16_bf16 v[66:81], v[158:161], v[106:109], v[66:81]
	ds_read_b128 v[158:161], v0 offset:27136
	ds_read_b128 v[150:153], v0 offset:27168
	ds_read_b128 v[142:145], v0 offset:22592
	ds_read_b128 v[138:141], v0 offset:27200
	ds_read_b128 v[134:137], v0 offset:22624
	ds_read_b128 v[130:133], v0 offset:27232
	s_waitcnt lgkmcnt(9)
	v_mfma_f32_32x32x16_bf16 v[50:65], v[186:189], v[106:109], v[50:65]
	v_mfma_f32_32x32x16_bf16 v[66:81], v[182:185], v[110:113], v[66:81]
	s_waitcnt lgkmcnt(8)
	v_mfma_f32_32x32x16_bf16 v[50:65], v[190:193], v[110:113], v[50:65]
	s_nop 9
	v_max_f32_e32 v0, v67, v67
	v_max_f32_e32 v182, v66, v66
	v_max_f32_e32 v0, v182, v0
	v_max3_f32 v182, v68, v69, v51
	v_max3_f32 v0, v0, v50, v52
	v_max3_f32 v0, v0, v53, v70
	v_max3_f32 v182, v182, v72, v73
	v_max3_f32 v0, v0, v71, v54
	v_max3_f32 v182, v182, v56, v57
	v_max3_f32 v0, v0, v55, v74
	v_max3_f32 v182, v182, v76, v77
	v_max3_f32 v0, v0, v75, v58
	v_max3_f32 v182, v182, v60, v61
	v_max3_f32 v0, v0, v59, v78
	v_max3_f32 v182, v182, v80, v81
	v_max3_f32 v0, v0, v79, v62
	v_max3_f32 v182, v182, v64, v65
	v_max3_f32 v0, v0, v63, v182
	v_mov_b32_e32 v182, v0
	s_nop 1
	v_permlane32_swap_b32_e32 v0, v182
	v_max_f32_e32 v182, v182, v182
	v_max_f32_e32 v0, v0, v0
	v_max_f32_e32 v0, v0, v182
	v_cmp_lt_f32_e32 vcc, 0x41000000, v0
	s_cbranch_vccz .Ldma_join_1
	v_max_f32_e32 v0, v0, v0
	v_max_f32_e32 v34, 0, v0
	v_exp_f32_e64 v0, -v34
	v_add_f32_e32 v180, v180, v34
	v_sub_f32_e32 v66, v66, v34
	v_sub_f32_e32 v67, v67, v34
	v_sub_f32_e32 v68, v68, v34
	v_sub_f32_e32 v69, v69, v34
	v_sub_f32_e32 v70, v70, v34
	v_sub_f32_e32 v71, v71, v34
	v_sub_f32_e32 v72, v72, v34
	v_sub_f32_e32 v73, v73, v34
	v_sub_f32_e32 v74, v74, v34
	v_sub_f32_e32 v75, v75, v34
	v_sub_f32_e32 v76, v76, v34
	v_sub_f32_e32 v77, v77, v34
	v_sub_f32_e32 v78, v78, v34
	v_sub_f32_e32 v79, v79, v34
	v_sub_f32_e32 v80, v80, v34
	v_sub_f32_e32 v81, v81, v34
	v_sub_f32_e32 v50, v50, v34
	v_sub_f32_e32 v51, v51, v34
	v_sub_f32_e32 v52, v52, v34
	v_sub_f32_e32 v53, v53, v34
	v_sub_f32_e32 v54, v54, v34
	v_sub_f32_e32 v55, v55, v34
	v_sub_f32_e32 v56, v56, v34
	v_sub_f32_e32 v57, v57, v34
	v_sub_f32_e32 v58, v58, v34
	v_sub_f32_e32 v59, v59, v34
	v_sub_f32_e32 v60, v60, v34
	v_sub_f32_e32 v61, v61, v34
	v_sub_f32_e32 v62, v62, v34
	v_sub_f32_e32 v63, v63, v34
	v_sub_f32_e32 v64, v64, v34
	v_sub_f32_e32 v65, v65, v34
	v_sub_f32_e32 v34, 0, v180
	v_pk_mul_f32 v[32:33], v[32:33], v[0:1] op_sel_hi:[1,0]
	v_pk_mul_f32 v[30:31], v[30:31], v[0:1] op_sel_hi:[1,0]
	v_pk_mul_f32 v[28:29], v[28:29], v[0:1] op_sel_hi:[1,0]
	v_pk_mul_f32 v[26:27], v[26:27], v[0:1] op_sel_hi:[1,0]
	v_pk_mul_f32 v[24:25], v[24:25], v[0:1] op_sel_hi:[1,0]
	v_pk_mul_f32 v[22:23], v[22:23], v[0:1] op_sel_hi:[1,0]
	v_pk_mul_f32 v[20:21], v[20:21], v[0:1] op_sel_hi:[1,0]
	v_pk_mul_f32 v[18:19], v[18:19], v[0:1] op_sel_hi:[1,0]
	v_pk_mul_f32 v[16:17], v[16:17], v[0:1] op_sel_hi:[1,0]
	v_pk_mul_f32 v[14:15], v[14:15], v[0:1] op_sel_hi:[1,0]
	v_pk_mul_f32 v[12:13], v[12:13], v[0:1] op_sel_hi:[1,0]
	v_pk_mul_f32 v[10:11], v[10:11], v[0:1] op_sel_hi:[1,0]
	v_pk_mul_f32 v[8:9], v[8:9], v[0:1] op_sel_hi:[1,0]
	v_pk_mul_f32 v[6:7], v[6:7], v[0:1] op_sel_hi:[1,0]
	v_pk_mul_f32 v[4:5], v[4:5], v[0:1] op_sel_hi:[1,0]
	v_pk_mul_f32 v[2:3], v[2:3], v[0:1] op_sel_hi:[1,0]
	v_pk_mul_f32 v[172:173], v[172:173], v[0:1] op_sel_hi:[1,0]
	v_mov_b32_e32 v35, v34
	v_mov_b32_e32 v36, v34
	v_mov_b32_e32 v37, v34
	v_mov_b32_e32 v38, v34
	v_mov_b32_e32 v39, v34
	v_mov_b32_e32 v40, v34
	v_mov_b32_e32 v41, v34
	v_mov_b32_e32 v42, v34
	v_mov_b32_e32 v43, v34
	v_mov_b32_e32 v44, v34
	v_mov_b32_e32 v45, v34
	v_mov_b32_e32 v46, v34
	v_mov_b32_e32 v47, v34
	v_mov_b32_e32 v48, v34
	v_mov_b32_e32 v49, v34

.Ldma_skip_1:
	s_waitcnt vmcnt(3)
	s_barrier
	s_mov_b32 m0, s60
	s_nop 0
	global_load_lds_dwordx4 v202, s[18:19]
	s_mov_b32 m0, s61
	s_nop 0
	global_load_lds_dwordx4 v203, s[18:19]
	s_mov_b32 m0, s66
	s_nop 0
	global_load_lds_dwordx4 v204, s[18:19]
	s_add_i32 s44, s13, 5
	s_cmp_lt_u32 s44, s7
	s_cbranch_scc0 .Ldma_noadv_2
	v_add_u32_e32 v202, v196, v202
	v_add_u32_e32 v203, v197, v203
	v_add_u32_e32 v204, v198, v204
.Ldma_noadv_2:
	s_add_i32 s44, s13, 2
	s_cmp_gt_i32 s44, s12
	s_cbranch_scc1 .Ldma_skip_2
	v_add3_u32 v0, v205, v170, s67
	ds_read_b128 v[50:53], v0
	ds_read_b128 v[130:133], v0 offset:32
	ds_read_b128 v[134:137], v0 offset:6656
	ds_read_b128 v[138:141], v0 offset:6688
	ds_read_b128 v[142:145], v0 offset:64
	ds_read_b128 v[146:149], v0 offset:96
	ds_read_b128 v[150:153], v0 offset:6720
	ds_read_b128 v[154:157], v0 offset:6752
	ds_read_b128 v[158:161], v0 offset:128
	ds_read_b128 v[182:185], v0 offset:160
	ds_read_b128 v[186:189], v0 offset:6784
	ds_read_b128 v[190:193], v0 offset:6816
	s_waitcnt lgkmcnt(11)
	v_mfma_f32_32x32x16_bf16 v[66:81], v[50:53], v[82:85], v[34:49]
	v_add_u32_e32 v0, s67, v206
	s_waitcnt lgkmcnt(9)
	v_mfma_f32_32x32x16_bf16 v[50:65], v[134:137], v[82:85], v[34:49]
	v_mfma_f32_32x32x16_bf16 v[66:81], v[130:133], v[90:93], v[66:81]
	s_waitcnt lgkmcnt(8)
	v_mfma_f32_32x32x16_bf16 v[50:65], v[138:141], v[90:93], v[50:65]
	s_waitcnt lgkmcnt(7)
	v_mfma_f32_32x32x16_bf16 v[66:81], v[142:145], v[94:97], v[66:81]
	s_waitcnt lgkmcnt(5)
	v_mfma_f32_32x32x16_bf16 v[50:65], v[150:153], v[94:97], v[50:65]
	v_mfma_f32_32x32x16_bf16 v[66:81], v[146:149], v[98:101], v[66:81]
	s_waitcnt lgkmcnt(4)
	v_mfma_f32_32x32x16_bf16 v[50:65], v[154:157], v[98:101], v[50:65]
	ds_read_b128 v[154:157], v0
	ds_read_b128 v[146:149], v0 offset:32
	s_waitcnt lgkmcnt(5)
	v_mfma_f32_32x32x16_bf16 v[66:81], v[158:161], v[106:109], v[66:81]
	ds_read_b128 v[158:161], v0 offset:4608
	ds_read_b128 v[150:153], v0 offset:4640
	ds_read_b128 v[142:145], v0 offset:64
	ds_read_b128 v[138:141], v0 offset:4672
	ds_read_b128 v[134:137], v0 offset:96
	ds_read_b128 v[130:133], v0 offset:4704
	s_waitcnt lgkmcnt(9)
	v_mfma_f32_32x32x16_bf16 v[50:65], v[186:189], v[106:109], v[50:65]
	v_mfma_f32_32x32x16_bf16 v[66:81], v[182:185], v[110:113], v[66:81]
	s_waitcnt lgkmcnt(8)
	v_mfma_f32_32x32x16_bf16 v[50:65], v[190:193], v[110:113], v[50:65]
	s_nop 9
	v_max_f32_e32 v0, v67, v67
	v_max_f32_e32 v182, v66, v66
	v_max_f32_e32 v0, v182, v0
	v_max3_f32 v182, v68, v69, v51
	v_max3_f32 v0, v0, v50, v52
	v_max3_f32 v0, v0, v53, v70
	v_max3_f32 v182, v182, v72, v73
	v_max3_f32 v0, v0, v71, v54
	v_max3_f32 v182, v182, v56, v57
	v_max3_f32 v0, v0, v55, v74
	v_max3_f32 v182, v182, v76, v77
	v_max3_f32 v0, v0, v75, v58
	v_max3_f32 v182, v182, v60, v61
	v_max3_f32 v0, v0, v59, v78
	v_max3_f32 v182, v182, v80, v81
	v_max3_f32 v0, v0, v79, v62
	v_max3_f32 v182, v182, v64, v65
	v_max3_f32 v0, v0, v63, v182
	v_mov_b32_e32 v182, v0
	s_nop 1
	v_permlane32_swap_b32_e32 v0, v182
	v_max_f32_e32 v182, v182, v182
	v_max_f32_e32 v0, v0, v0
	v_max_f32_e32 v0, v0, v182
	v_cmp_lt_f32_e32 vcc, 0x41000000, v0
	s_cbranch_vccz .Ldma_join_2
	v_max_f32_e32 v0, v0, v0
	v_max_f32_e32 v34, 0, v0
	v_exp_f32_e64 v0, -v34
	v_add_f32_e32 v180, v180, v34
	v_sub_f32_e32 v66, v66, v34
	v_sub_f32_e32 v67, v67, v34
	v_sub_f32_e32 v68, v68, v34
	v_sub_f32_e32 v69, v69, v34
	v_sub_f32_e32 v70, v70, v34
	v_sub_f32_e32 v71, v71, v34
	v_sub_f32_e32 v72, v72, v34
	v_sub_f32_e32 v73, v73, v34
	v_sub_f32_e32 v74, v74, v34
	v_sub_f32_e32 v75, v75, v34
	v_sub_f32_e32 v76, v76, v34
	v_sub_f32_e32 v77, v77, v34
	v_sub_f32_e32 v78, v78, v34
	v_sub_f32_e32 v79, v79, v34
	v_sub_f32_e32 v80, v80, v34
	v_sub_f32_e32 v81, v81, v34
	v_sub_f32_e32 v50, v50, v34
	v_sub_f32_e32 v51, v51, v34
	v_sub_f32_e32 v52, v52, v34
	v_sub_f32_e32 v53, v53, v34
	v_sub_f32_e32 v54, v54, v34
	v_sub_f32_e32 v55, v55, v34
	v_sub_f32_e32 v56, v56, v34
	v_sub_f32_e32 v57, v57, v34
	v_sub_f32_e32 v58, v58, v34
	v_sub_f32_e32 v59, v59, v34
	v_sub_f32_e32 v60, v60, v34
	v_sub_f32_e32 v61, v61, v34
	v_sub_f32_e32 v62, v62, v34
	v_sub_f32_e32 v63, v63, v34
	v_sub_f32_e32 v64, v64, v34
	v_sub_f32_e32 v65, v65, v34
	v_sub_f32_e32 v34, 0, v180
	v_pk_mul_f32 v[32:33], v[32:33], v[0:1] op_sel_hi:[1,0]
	v_pk_mul_f32 v[30:31], v[30:31], v[0:1] op_sel_hi:[1,0]
	v_pk_mul_f32 v[28:29], v[28:29], v[0:1] op_sel_hi:[1,0]
	v_pk_mul_f32 v[26:27], v[26:27], v[0:1] op_sel_hi:[1,0]
	v_pk_mul_f32 v[24:25], v[24:25], v[0:1] op_sel_hi:[1,0]
	v_pk_mul_f32 v[22:23], v[22:23], v[0:1] op_sel_hi:[1,0]
	v_pk_mul_f32 v[20:21], v[20:21], v[0:1] op_sel_hi:[1,0]
	v_pk_mul_f32 v[18:19], v[18:19], v[0:1] op_sel_hi:[1,0]
	v_pk_mul_f32 v[16:17], v[16:17], v[0:1] op_sel_hi:[1,0]
	v_pk_mul_f32 v[14:15], v[14:15], v[0:1] op_sel_hi:[1,0]
	v_pk_mul_f32 v[12:13], v[12:13], v[0:1] op_sel_hi:[1,0]
	v_pk_mul_f32 v[10:11], v[10:11], v[0:1] op_sel_hi:[1,0]
	v_pk_mul_f32 v[8:9], v[8:9], v[0:1] op_sel_hi:[1,0]
	v_pk_mul_f32 v[6:7], v[6:7], v[0:1] op_sel_hi:[1,0]
	v_pk_mul_f32 v[4:5], v[4:5], v[0:1] op_sel_hi:[1,0]
	v_pk_mul_f32 v[2:3], v[2:3], v[0:1] op_sel_hi:[1,0]
	v_pk_mul_f32 v[172:173], v[172:173], v[0:1] op_sel_hi:[1,0]
	v_mov_b32_e32 v35, v34
	v_mov_b32_e32 v36, v34
	v_mov_b32_e32 v37, v34
	v_mov_b32_e32 v38, v34
	v_mov_b32_e32 v39, v34
	v_mov_b32_e32 v40, v34
	v_mov_b32_e32 v41, v34
	v_mov_b32_e32 v42, v34
	v_mov_b32_e32 v43, v34
	v_mov_b32_e32 v44, v34
	v_mov_b32_e32 v45, v34
	v_mov_b32_e32 v46, v34
	v_mov_b32_e32 v47, v34
	v_mov_b32_e32 v48, v34
	v_mov_b32_e32 v49, v34

.Ldma_skip_2:
	s_waitcnt vmcnt(3)
	s_barrier
	s_add_u32 m0, s60, 0x5800
	s_nop 0
	global_load_lds_dwordx4 v202, s[18:19]
	s_add_u32 m0, s61, 0x5800
	s_nop 0
	global_load_lds_dwordx4 v203, s[18:19]
	s_add_u32 m0, s66, 0x5800
	s_nop 0
	global_load_lds_dwordx4 v204, s[18:19]
	s_add_i32 s44, s13, 6
	s_cmp_lt_u32 s44, s7
	s_cbranch_scc0 .Ldma_noadv_3
	v_add_u32_e32 v202, v196, v202
	v_add_u32_e32 v203, v197, v203
	v_add_u32_e32 v204, v198, v204
.Ldma_noadv_3:
	s_add_i32 s44, s13, 3
	s_cmp_gt_i32 s44, s12
	s_cbranch_scc1 .Ldma_skip_3
	v_add3_u32 v0, v205, v170, s67
	ds_read_b128 v[50:53], v0 offset:22528
	ds_read_b128 v[130:133], v0 offset:22560
	ds_read_b128 v[134:137], v0 offset:29184
	ds_read_b128 v[138:141], v0 offset:29216
	ds_read_b128 v[142:145], v0 offset:22592
	ds_read_b128 v[146:149], v0 offset:22624
	ds_read_b128 v[150:153], v0 offset:29248
	ds_read_b128 v[154:157], v0 offset:29280
	ds_read_b128 v[158:161], v0 offset:22656
	ds_read_b128 v[182:185], v0 offset:22688
	ds_read_b128 v[186:189], v0 offset:29312
	ds_read_b128 v[190:193], v0 offset:29344
	s_waitcnt lgkmcnt(11)
	v_mfma_f32_32x32x16_bf16 v[66:81], v[50:53], v[82:85], v[34:49]
	v_add_u32_e32 v0, s67, v206
	s_waitcnt lgkmcnt(9)
	v_mfma_f32_32x32x16_bf16 v[50:65], v[134:137], v[82:85], v[34:49]
	v_mfma_f32_32x32x16_bf16 v[66:81], v[130:133], v[90:93], v[66:81]
	s_waitcnt lgkmcnt(8)
	v_mfma_f32_32x32x16_bf16 v[50:65], v[138:141], v[90:93], v[50:65]
	s_waitcnt lgkmcnt(7)
	v_mfma_f32_32x32x16_bf16 v[66:81], v[142:145], v[94:97], v[66:81]
	s_waitcnt lgkmcnt(5)
	v_mfma_f32_32x32x16_bf16 v[50:65], v[150:153], v[94:97], v[50:65]
	v_mfma_f32_32x32x16_bf16 v[66:81], v[146:149], v[98:101], v[66:81]
	s_waitcnt lgkmcnt(4)
	v_mfma_f32_32x32x16_bf16 v[50:65], v[154:157], v[98:101], v[50:65]
	ds_read_b128 v[154:157], v0 offset:22528
	ds_read_b128 v[146:149], v0 offset:22560
	s_waitcnt lgkmcnt(5)
	v_mfma_f32_32x32x16_bf16 v[66:81], v[158:161], v[106:109], v[66:81]
	ds_read_b128 v[158:161], v0 offset:27136
	ds_read_b128 v[150:153], v0 offset:27168
	ds_read_b128 v[142:145], v0 offset:22592
	ds_read_b128 v[138:141], v0 offset:27200
	ds_read_b128 v[134:137], v0 offset:22624
	ds_read_b128 v[130:133], v0 offset:27232
	s_waitcnt lgkmcnt(9)
	v_mfma_f32_32x32x16_bf16 v[50:65], v[186:189], v[106:109], v[50:65]
	v_mfma_f32_32x32x16_bf16 v[66:81], v[182:185], v[110:113], v[66:81]
	s_waitcnt lgkmcnt(8)
	v_mfma_f32_32x32x16_bf16 v[50:65], v[190:193], v[110:113], v[50:65]
	s_nop 9
	v_max_f32_e32 v0, v67, v67
	v_max_f32_e32 v182, v66, v66
	v_max_f32_e32 v0, v182, v0
	v_max3_f32 v182, v68, v69, v51
	v_max3_f32 v0, v0, v50, v52
	v_max3_f32 v0, v0, v53, v70
	v_max3_f32 v182, v182, v72, v73
	v_max3_f32 v0, v0, v71, v54
	v_max3_f32 v182, v182, v56, v57
	v_max3_f32 v0, v0, v55, v74
	v_max3_f32 v182, v182, v76, v77
	v_max3_f32 v0, v0, v75, v58
	v_max3_f32 v182, v182, v60, v61
	v_max3_f32 v0, v0, v59, v78
	v_max3_f32 v182, v182, v80, v81
	v_max3_f32 v0, v0, v79, v62
	v_max3_f32 v182, v182, v64, v65
	v_max3_f32 v0, v0, v63, v182
	v_mov_b32_e32 v182, v0
	s_nop 1
	v_permlane32_swap_b32_e32 v0, v182
	v_max_f32_e32 v182, v182, v182
	v_max_f32_e32 v0, v0, v0
	v_max_f32_e32 v0, v0, v182
	v_cmp_lt_f32_e32 vcc, 0x41000000, v0
	s_cbranch_vccz .Ldma_join_3
	v_max_f32_e32 v0, v0, v0
	v_max_f32_e32 v34, 0, v0
	v_exp_f32_e64 v0, -v34
	v_add_f32_e32 v180, v180, v34
	v_sub_f32_e32 v66, v66, v34
	v_sub_f32_e32 v67, v67, v34
	v_sub_f32_e32 v68, v68, v34
	v_sub_f32_e32 v69, v69, v34
	v_sub_f32_e32 v70, v70, v34
	v_sub_f32_e32 v71, v71, v34
	v_sub_f32_e32 v72, v72, v34
	v_sub_f32_e32 v73, v73, v34
	v_sub_f32_e32 v74, v74, v34
	v_sub_f32_e32 v75, v75, v34
	v_sub_f32_e32 v76, v76, v34
	v_sub_f32_e32 v77, v77, v34
	v_sub_f32_e32 v78, v78, v34
	v_sub_f32_e32 v79, v79, v34
	v_sub_f32_e32 v80, v80, v34
	v_sub_f32_e32 v81, v81, v34
	v_sub_f32_e32 v50, v50, v34
	v_sub_f32_e32 v51, v51, v34
	v_sub_f32_e32 v52, v52, v34
	v_sub_f32_e32 v53, v53, v34
	v_sub_f32_e32 v54, v54, v34
	v_sub_f32_e32 v55, v55, v34
	v_sub_f32_e32 v56, v56, v34
	v_sub_f32_e32 v57, v57, v34
	v_sub_f32_e32 v58, v58, v34
	v_sub_f32_e32 v59, v59, v34
	v_sub_f32_e32 v60, v60, v34
	v_sub_f32_e32 v61, v61, v34
	v_sub_f32_e32 v62, v62, v34
	v_sub_f32_e32 v63, v63, v34
	v_sub_f32_e32 v64, v64, v34
	v_sub_f32_e32 v65, v65, v34
	v_sub_f32_e32 v34, 0, v180
	v_pk_mul_f32 v[32:33], v[32:33], v[0:1] op_sel_hi:[1,0]
	v_pk_mul_f32 v[30:31], v[30:31], v[0:1] op_sel_hi:[1,0]
	v_pk_mul_f32 v[28:29], v[28:29], v[0:1] op_sel_hi:[1,0]
	v_pk_mul_f32 v[26:27], v[26:27], v[0:1] op_sel_hi:[1,0]
	v_pk_mul_f32 v[24:25], v[24:25], v[0:1] op_sel_hi:[1,0]
	v_pk_mul_f32 v[22:23], v[22:23], v[0:1] op_sel_hi:[1,0]
	v_pk_mul_f32 v[20:21], v[20:21], v[0:1] op_sel_hi:[1,0]
	v_pk_mul_f32 v[18:19], v[18:19], v[0:1] op_sel_hi:[1,0]
	v_pk_mul_f32 v[16:17], v[16:17], v[0:1] op_sel_hi:[1,0]
	v_pk_mul_f32 v[14:15], v[14:15], v[0:1] op_sel_hi:[1,0]
	v_pk_mul_f32 v[12:13], v[12:13], v[0:1] op_sel_hi:[1,0]
	v_pk_mul_f32 v[10:11], v[10:11], v[0:1] op_sel_hi:[1,0]
	v_pk_mul_f32 v[8:9], v[8:9], v[0:1] op_sel_hi:[1,0]
	v_pk_mul_f32 v[6:7], v[6:7], v[0:1] op_sel_hi:[1,0]
	v_pk_mul_f32 v[4:5], v[4:5], v[0:1] op_sel_hi:[1,0]
	v_pk_mul_f32 v[2:3], v[2:3], v[0:1] op_sel_hi:[1,0]
	v_pk_mul_f32 v[172:173], v[172:173], v[0:1] op_sel_hi:[1,0]
	v_mov_b32_e32 v35, v34
	v_mov_b32_e32 v36, v34
	v_mov_b32_e32 v37, v34
	v_mov_b32_e32 v38, v34
	v_mov_b32_e32 v39, v34
	v_mov_b32_e32 v40, v34
	v_mov_b32_e32 v41, v34
	v_mov_b32_e32 v42, v34
	v_mov_b32_e32 v43, v34
	v_mov_b32_e32 v44, v34
	v_mov_b32_e32 v45, v34
	v_mov_b32_e32 v46, v34
	v_mov_b32_e32 v47, v34
	v_mov_b32_e32 v48, v34
	v_mov_b32_e32 v49, v34

.Ldma_skip_3:
	s_waitcnt vmcnt(3)
	s_barrier
	s_add_i32 s13, s13, 4
	s_cmp_lt_u32 s13, s7
	s_cbranch_scc1 .Ldma_top
	s_waitcnt vmcnt(0)
	s_barrier
	s_branch .LBB0_966

	.amdhsa_kernel _Z14fwd_megakernel6Params
		.amdhsa_group_segment_fixed_size 0
		.amdhsa_private_segment_fixed_size 0
		.amdhsa_kernarg_size 528
		.amdhsa_user_sgpr_count 2
		.amdhsa_user_sgpr_dispatch_ptr 0
		.amdhsa_user_sgpr_queue_ptr 0
		.amdhsa_user_sgpr_kernarg_segment_ptr 1
		.amdhsa_user_sgpr_dispatch_id 0
		.amdhsa_user_sgpr_kernarg_preload_length 0
		.amdhsa_user_sgpr_kernarg_preload_offset 0
		.amdhsa_user_sgpr_private_segment_size 0
		.amdhsa_uses_dynamic_stack 0
		.amdhsa_enable_private_segment 0
		.amdhsa_system_sgpr_workgroup_id_x 1
		.amdhsa_system_sgpr_workgroup_id_y 0
		.amdhsa_system_sgpr_workgroup_id_z 0
		.amdhsa_system_sgpr_workgroup_info 0
		.amdhsa_system_vgpr_workitem_id 2
		.amdhsa_next_free_vgpr 256
		.amdhsa_next_free_sgpr 102
		.amdhsa_accum_offset 256
		.amdhsa_reserve_vcc 1
		.amdhsa_float_round_mode_32 0
		.amdhsa_float_round_mode_16_64 0
		.amdhsa_float_denorm_mode_32 3
		.amdhsa_float_denorm_mode_16_64 3
		.amdhsa_dx10_clamp 1
		.amdhsa_ieee_mode 1
		.amdhsa_fp16_overflow 0
		.amdhsa_tg_split 0
		.amdhsa_exception_fp_ieee_invalid_op 0
		.amdhsa_exception_fp_denorm_src 0
		.amdhsa_exception_fp_ieee_div_zero 0
		.amdhsa_exception_fp_ieee_overflow 0
		.amdhsa_exception_fp_ieee_underflow 0
		.amdhsa_exception_fp_ieee_inexact 0
		.amdhsa_exception_int_div_zero 0
	.end_amdhsa_kernel

amdhsa.kernels:
  - .agpr_count:     0
    .args:
      - .offset:         0
        .size:           272
        .value_kind:     by_value
      - .offset:         272
        .size:           4
        .value_kind:     hidden_block_count_x
      - .offset:         276
        .size:           4
        .value_kind:     hidden_block_count_y
      - .offset:         280
        .size:           4
        .value_kind:     hidden_block_count_z
      - .offset:         284
        .size:           2
        .value_kind:     hidden_group_size_x
      - .offset:         286
        .size:           2
        .value_kind:     hidden_group_size_y
      - .offset:         288
        .size:           2
        .value_kind:     hidden_group_size_z
      - .offset:         290
        .size:           2
        .value_kind:     hidden_remainder_x
      - .offset:         292
        .size:           2
        .value_kind:     hidden_remainder_y
      - .offset:         294
        .size:           2
        .value_kind:     hidden_remainder_z
      - .offset:         312
        .size:           8
        .value_kind:     hidden_global_offset_x
      - .offset:         320
        .size:           8
        .value_kind:     hidden_global_offset_y
      - .offset:         328
        .size:           8
        .value_kind:     hidden_global_offset_z
      - .offset:         336
        .size:           2
        .value_kind:     hidden_grid_dims
      - .offset:         360
        .size:           8
        .value_kind:     hidden_multigrid_sync_arg
      - .offset:         392
        .size:           4
        .value_kind:     hidden_dynamic_lds_size
    .group_segment_fixed_size: 0
    .kernarg_segment_align: 8
    .kernarg_segment_size: 528
    .language:       OpenCL C
    .language_version:
      - 2
      - 0
    .max_flat_workgroup_size: 512
    .name:           _Z14fwd_megakernel6Params
    .private_segment_fixed_size: 0
    .sgpr_count:     108
    .sgpr_spill_count: 68
    .symbol:         _Z14fwd_megakernel6Params.kd
    .uniform_work_group_size: 1
    .uses_dynamic_stack: false
    .vgpr_count:     256
    .vgpr_spill_count: 0
    .wavefront_size: 64
